# attention: next-tile p0 exps issued speculatively in the last PV MFMA group shadow (rare rescale path recomputes them)
# baseline (speedup 1.0000x reference)
; __device__ __forceinline__ void finishSM(f32x16& p0, f32x16& p1, float alpha, float& l_reg, bf16x8& pa0, bf16x8& pa1, bf16x8& pa2, bf16x8& pa3) {
;   for (int r = 0; r < 16; ++r) p1[r] = __builtin_amdgcn_exp2f(p1[r]);
;   float ps = 0; for (int r = 0; r < 16; ++r) ps += p0[r]; for (int r = 0; r < 16; ++r) ps += p1[r];
;   { auto rr = __builtin_amdgcn_permlane32_swap(__float_as_uint(ps), __float_as_uint(ps), false, false);
;     ps = __uint_as_float(rr[0]) + __uint_as_float(rr[1]); }
;   l_reg = l_reg * alpha + ps;
;     ...
;   PK4(p0, 0, pa0); PK4(p0, 8, pa1); PK4(p1, 0, pa2); PK4(p1, 8, pa3);
;     ...
; }
; __device__ __forceinline__ void qkt(f32x16& p0, f32x16& p1, const bf16* Ks, const bf16x8* qr, const f32x16& negm, int r32, int hi) {
; #pragma unroll
;   for (int d0 = 0; d0 < 8; ++d0) { int cb = (d0 * 16 + hi * 8) * 2;
;     bf16x8 b0 = *reinterpret_cast<const bf16x8*>((const char*)Ks + KSWZ(r32, cb));
;     bf16x8 b1 = *reinterpret_cast<const bf16x8*>((const char*)Ks + KSWZ(32 + r32, cb));
;     if (d0 == 0) { p0 = __builtin_amdgcn_mfma_f32_32x32x16_bf16(b0, qr[0], negm, 0, 0, 0); p1 = __builtin_amdgcn_mfma_f32_32x32x16_bf16(b1, qr[0], negm, 0, 0, 0); }
;     else { p0 = __builtin_amdgcn_mfma_f32_32x32x16_bf16(b0, qr[d0], p0, 0, 0, 0); p1 = __builtin_amdgcn_mfma_f32_32x32x16_bf16(b1, qr[d0], p1, 0, 0, 0); } }
; }
; __device__ __forceinline__ int v_st(int k, int c) { const int kk = (k & ~0xC) | ((k & 4) << 1) | ((k & 8) >> 1); return ((kk >> 3) * 4 + (c >> 5)) * 512 + ((kk & 7) * 32 + (c & 31)) * 2; }
; __device__ __forceinline__ int v_rd_base(int lane) { return ((lane & 3) << 3) | (((lane >> 2) & 3) << 6) | (((lane >> 4) & 1) << 5) | (((lane >> 5) & 1) << 8); }
; template <int OFF> __device__ __forceinline__ s16x4 tr_read(int vb) {
;   s16x4 r; asm volatile("ds_read_b64_tr_b16 %0, %1 offset:%2" : "=&v"(r) : "v"(vb), "i"(OFF) : "memory"); return r;
; }
; template <int D0> __device__ __forceinline__ void pv_one(f32x16& od, int vb, bf16x8 pa0, bf16x8 pa1, bf16x8 pa2, bf16x8 pa3) {
;   const s16x4 l0 = tr_read<v_rd_off(D0, 0, 0)>(vb), h0 = tr_read<v_rd_off(D0, 0, 1)>(vb), l1 = tr_read<v_rd_off(D0, 1, 0)>(vb), h1 = tr_read<v_rd_off(D0, 1, 1)>(vb);
;   const s16x4 l2 = tr_read<v_rd_off(D0, 2, 0)>(vb), h2 = tr_read<v_rd_off(D0, 2, 1)>(vb), l3 = tr_read<v_rd_off(D0, 3, 0)>(vb), h3 = tr_read<v_rd_off(D0, 3, 1)>(vb);
.LBB0_96:
	ds_read_b128 v[230:233], v216 offset:57344
	ds_read_b128 v[112:115], v216 offset:49152
	v_add_f32_e32 v178, 0, v245
	v_add_f32_e32 v178, v247, v178
	v_add_f32_e32 v178, v179, v178
	v_add_f32_e32 v178, v246, v178
	s_waitcnt lgkmcnt(0)
	v_mfma_f32_32x32x16_bf16 v[128:143], v[112:115], v[146:149], v[80:95]
	v_add_f32_e32 v178, v180, v178
	v_add_f32_e32 v178, v244, v178
	v_mfma_f32_32x32x16_bf16 v[112:127], v[230:233], v[146:149], v[80:95]
	ds_read_b128 v[230:233], v224 offset:57344
	ds_read_b128 v[248:251], v224 offset:49152
	v_add_f32_e32 v178, v181, v178
	v_add_f32_e32 v178, v243, v178
	v_add_f32_e32 v178, v240, v178
	v_add_f32_e32 v178, v242, v178
	v_add_f32_e32 v178, v239, v178
	v_add_f32_e32 v178, v241, v178
	s_waitcnt lgkmcnt(0)
	v_mfma_f32_32x32x16_bf16 v[128:143], v[248:251], v[150:153], v[128:143]
	v_exp_f32_e32 v96, v96
	v_add_f32_e32 v178, v236, v178
	v_exp_f32_e32 v97, v97
	v_add_f32_e32 v178, v238, v178
	v_exp_f32_e32 v98, v98
	v_add_f32_e32 v178, v235, v178
	v_exp_f32_e32 v99, v99
	v_mfma_f32_32x32x16_bf16 v[112:127], v[230:233], v[150:153], v[112:127]
	ds_read_b128 v[230:233], v223 offset:57344
	ds_read_b128 v[248:251], v223 offset:49152
	v_add_f32_e32 v178, v237, v178
	v_exp_f32_e32 v100, v100
	v_add_f32_e32 v178, v96, v178
	v_exp_f32_e32 v101, v101
	v_add_f32_e32 v178, v97, v178
	v_exp_f32_e32 v102, v102
	s_waitcnt lgkmcnt(0)
	v_mfma_f32_32x32x16_bf16 v[128:143], v[248:251], v[154:157], v[128:143]
	v_add_f32_e32 v178, v98, v178
	v_exp_f32_e32 v103, v103
	v_add_f32_e32 v178, v99, v178
	v_exp_f32_e32 v104, v104
	v_add_f32_e32 v178, v100, v178
	v_exp_f32_e32 v105, v105
	v_add_f32_e32 v178, v101, v178
	v_mfma_f32_32x32x16_bf16 v[112:127], v[230:233], v[154:157], v[112:127]
	ds_read_b128 v[230:233], v221 offset:57344
	ds_read_b128 v[248:251], v221 offset:49152
	v_exp_f32_e32 v106, v106
	v_add_f32_e32 v178, v102, v178
	v_exp_f32_e32 v107, v107
	v_add_f32_e32 v178, v103, v178
	v_exp_f32_e32 v108, v108
	v_add_f32_e32 v178, v104, v178
	s_waitcnt lgkmcnt(0)
	v_mfma_f32_32x32x16_bf16 v[128:143], v[248:251], v[158:161], v[128:143]
	v_exp_f32_e32 v109, v109
	v_add_f32_e32 v178, v105, v178
	v_exp_f32_e32 v110, v110
	v_add_f32_e32 v178, v106, v178
	v_exp_f32_e32 v111, v111
	v_add_f32_e32 v178, v107, v178
	v_add_f32_e32 v178, v108, v178
	v_mfma_f32_32x32x16_bf16 v[112:127], v[230:233], v[158:161], v[112:127]
	ds_read_b128 v[230:233], v222 offset:57344
	ds_read_b128 v[248:251], v222 offset:49152
	v_add_f32_e32 v178, v109, v178
	v_add_f32_e32 v178, v110, v178
	s_waitcnt lgkmcnt(0)
	v_mfma_f32_32x32x16_bf16 v[128:143], v[248:251], v[162:165], v[128:143]
	v_mfma_f32_32x32x16_bf16 v[112:127], v[230:233], v[162:165], v[112:127]
	ds_read_b128 v[230:233], v225 offset:57344
	ds_read_b128 v[248:251], v225 offset:49152
	s_waitcnt lgkmcnt(0)
	v_mfma_f32_32x32x16_bf16 v[128:143], v[248:251], v[166:169], v[128:143]
	v_mfma_f32_32x32x16_bf16 v[112:127], v[230:233], v[166:169], v[112:127]
	ds_read_b128 v[230:233], v226 offset:57344
	ds_read_b128 v[248:251], v226 offset:49152
	s_waitcnt lgkmcnt(0)
	v_mfma_f32_32x32x16_bf16 v[128:143], v[248:251], v[170:173], v[128:143]
	v_mfma_f32_32x32x16_bf16 v[112:127], v[230:233], v[170:173], v[112:127]
	ds_read_b128 v[230:233], v227 offset:57344
	ds_read_b128 v[248:251], v227 offset:49152
	s_waitcnt lgkmcnt(0)
	v_mfma_f32_32x32x16_bf16 v[128:143], v[248:251], v[174:177], v[128:143]
	v_mfma_f32_32x32x16_bf16 v[112:127], v[230:233], v[174:177], v[112:127]
	v_add_f32_e32 v230, v111, v178
	v_mov_b32_e32 v231, v230
	v_cvt_pk_bf16_f32 v178, v245, v247
	v_cvt_pk_bf16_f32 v179, v179, v246
	v_cvt_pk_bf16_f32 v180, v180, v244
	s_nop 1
	v_permlane32_swap_b32_e32 v230, v231
	v_cvt_pk_bf16_f32 v181, v181, v243
	v_permlane32_swap_b32_e32 v178, v180
	v_cvt_pk_bf16_f32 v232, v240, v242
	v_cvt_pk_bf16_f32 v233, v239, v241
	v_cvt_pk_bf16_f32 v234, v236, v238
	v_cvt_pk_bf16_f32 v235, v235, v237
	v_cvt_pk_bf16_f32 v236, v96, v97
	v_cvt_pk_bf16_f32 v237, v98, v99
	v_cvt_pk_bf16_f32 v238, v100, v101
	v_cvt_pk_bf16_f32 v239, v102, v103
	v_cvt_pk_bf16_f32 v240, v104, v105
	v_cvt_pk_bf16_f32 v241, v106, v107
	v_cvt_pk_bf16_f32 v242, v108, v109
	v_cvt_pk_bf16_f32 v243, v110, v111
	v_permlane32_swap_b32_e32 v179, v181
	v_permlane32_swap_b32_e32 v232, v234
	v_permlane32_swap_b32_e32 v233, v235
	v_permlane32_swap_b32_e32 v236, v238
	v_permlane32_swap_b32_e32 v237, v239
	v_permlane32_swap_b32_e32 v240, v242
	v_permlane32_swap_b32_e32 v241, v243
	s_add_i32 s25, s1, 0xffff8000
	s_mov_b32 s58, s90
	s_mov_b32 s59, s91
	ds_read_b64_tr_b16 v[244:245], v213 offset:0
	ds_read_b64_tr_b16 v[246:247], v213 offset:0x800
	ds_read_b64_tr_b16 v[248:249], v213 offset:0x1000
	ds_read_b64_tr_b16 v[250:251], v213 offset:0x1800
	ds_read_b64_tr_b16 v[186:187], v213 offset:0x2000
	ds_read_b64_tr_b16 v[188:189], v213 offset:0x2800
	ds_read_b64_tr_b16 v[204:205], v213 offset:0x3000
	ds_read_b64_tr_b16 v[206:207], v213 offset:0x3800
	s_waitcnt lgkmcnt(0)
; template <bool FIRST>
; __device__ __forceinline__ void partialSM(f32x16& p0, f32x16& p1, float& m_reg, f32x16& negm, float& alpha) {
;   float pmax = p0[0]; for (int r = 1; r < 16; ++r) pmax = fmaxf(pmax, p0[r]); for (int r = 0; r < 16; ++r) pmax = fmaxf(pmax, p1[r]);
;   { auto rr = __builtin_amdgcn_permlane32_swap(__float_as_uint(pmax), __float_as_uint(pmax), false, false);
;     pmax = fmaxf(__uint_as_float(rr[0]), __uint_as_float(rr[1])); }
;   if (!FIRST && __builtin_expect(__all(pmax <= THRL), 1)) { alpha = 1.f; }
;   else {
;     const float d = FIRST ? pmax : fmaxf(pmax, 0.f);
;     alpha = FIRST ? 1.f : __builtin_amdgcn_exp2f(-d);
;     m_reg += d;
;     for (int r = 0; r < 16; ++r) p0[r] -= d; for (int r = 0; r < 16; ++r) p1[r] -= d;
;     const float nm = -m_reg; for (int r = 0; r < 16; ++r) negm[r] = nm;
;   }
;   for (int r = 0; r < 16; ++r) p0[r] = __builtin_amdgcn_exp2f(p0[r]);
	s_nop 0
	v_mfma_f32_32x32x16_bf16 v[0:15], v[178:181], v[244:247], v[0:15]
	v_mfma_f32_32x32x16_bf16 v[0:15], v[232:235], v[248:251], v[0:15]
	v_mfma_f32_32x32x16_bf16 v[0:15], v[236:239], v[186:189], v[0:15]
	ds_read_b64_tr_b16 v[186:187], v213 offset:0x200
	ds_read_b64_tr_b16 v[188:189], v213 offset:0xa00
	v_mfma_f32_32x32x16_bf16 v[0:15], v[240:243], v[204:207], v[0:15]
	ds_read_b64_tr_b16 v[204:205], v213 offset:0x1200
	ds_read_b64_tr_b16 v[206:207], v213 offset:0x1a00
	ds_read_b64_tr_b16 v[244:245], v213 offset:0x2200
	ds_read_b64_tr_b16 v[246:247], v213 offset:0x2a00
	ds_read_b64_tr_b16 v[248:249], v213 offset:0x3200
	ds_read_b64_tr_b16 v[250:251], v213 offset:0x3a00
	s_add_i32 m0, s98, 0x8000
	s_nop 0
	buffer_load_dwordx4 v64, s[56:59], s25 offen lds
	s_add_i32 m0, s98, 0x8400
	s_nop 0
	buffer_load_dwordx4 v65, s[56:59], s25 offen lds
	s_waitcnt lgkmcnt(0)
	v_mfma_f32_32x32x16_bf16 v[32:47], v[178:181], v[186:189], v[32:47]
	ds_read_b64_tr_b16 v[186:187], v213 offset:0x400
	ds_read_b64_tr_b16 v[188:189], v213 offset:0xc00
	v_mfma_f32_32x32x16_bf16 v[32:47], v[232:235], v[204:207], v[32:47]
	ds_read_b64_tr_b16 v[204:205], v213 offset:0x1400
	ds_read_b64_tr_b16 v[206:207], v213 offset:0x1c00
	v_mfma_f32_32x32x16_bf16 v[32:47], v[236:239], v[244:247], v[32:47]
	ds_read_b64_tr_b16 v[244:245], v213 offset:0x2400
	ds_read_b64_tr_b16 v[246:247], v213 offset:0x2c00
	v_mfma_f32_32x32x16_bf16 v[32:47], v[240:243], v[248:251], v[32:47]
	ds_read_b64_tr_b16 v[248:249], v213 offset:0x3400
	ds_read_b64_tr_b16 v[250:251], v213 offset:0x3c00
	s_waitcnt lgkmcnt(0)
	v_mfma_f32_32x32x16_bf16 v[16:31], v[178:181], v[186:189], v[16:31]
	ds_read_b64_tr_b16 v[186:187], v213 offset:0x600
	ds_read_b64_tr_b16 v[188:189], v213 offset:0xe00
	v_mfma_f32_32x32x16_bf16 v[16:31], v[232:235], v[204:207], v[16:31]
	ds_read_b64_tr_b16 v[204:205], v213 offset:0x1600
	ds_read_b64_tr_b16 v[206:207], v213 offset:0x1e00
	v_mfma_f32_32x32x16_bf16 v[16:31], v[236:239], v[244:247], v[16:31]
	ds_read_b64_tr_b16 v[244:245], v213 offset:0x2600
	ds_read_b64_tr_b16 v[246:247], v213 offset:0x2e00
	v_mfma_f32_32x32x16_bf16 v[16:31], v[240:243], v[248:251], v[16:31]
	ds_read_b64_tr_b16 v[248:249], v213 offset:0x3600
	ds_read_b64_tr_b16 v[250:251], v213 offset:0x3e00
	s_waitcnt lgkmcnt(0)
	s_barrier
	v_mfma_f32_32x32x16_bf16 v[48:63], v[178:181], v[186:189], v[48:63]
	s_mov_b32 m0, s98
	s_nop 0
	buffer_load_dwordx4 v66, s[88:91], s25 offen lds
	v_max_f32_e32 v74, v129, v129
	v_max_f32_e32 v75, v128, v128
	v_max_f32_e32 v74, v75, v74
	v_exp_f32_e32 v178, v128
	v_exp_f32_e32 v179, v130
	v_max3_f32 v74, v74, v130, v131
	v_max3_f32 v74, v74, v132, v133
	v_exp_f32_e32 v180, v132
	v_exp_f32_e32 v181, v134
	v_max3_f32 v74, v74, v134, v135
	v_max3_f32 v74, v74, v136, v137
	v_mfma_f32_32x32x16_bf16 v[48:63], v[232:235], v[204:207], v[48:63]
	s_add_i32 m0, s98, 0x400
	s_nop 0
	buffer_load_dwordx4 v67, s[88:91], s25 offen lds
	v_exp_f32_e32 v235, v142
	v_max3_f32 v74, v74, v138, v139
	v_max3_f32 v74, v74, v140, v141
	v_max3_f32 v74, v74, v142, v143
	v_max3_f32 v74, v74, v112, v113
	v_max3_f32 v74, v74, v114, v115
	v_max3_f32 v74, v74, v116, v117
	v_max3_f32 v74, v74, v118, v119
	v_mfma_f32_32x32x16_bf16 v[48:63], v[236:239], v[244:247], v[48:63]
	v_exp_f32_e32 v236, v140
	v_exp_f32_e32 v238, v141
	v_exp_f32_e32 v239, v138
	v_exp_f32_e32 v237, v143
	v_max3_f32 v74, v74, v120, v121
	v_max3_f32 v74, v74, v122, v123
	v_exp_f32_e32 v246, v129
	v_exp_f32_e32 v245, v131
	v_exp_f32_e32 v244, v133
	v_max3_f32 v74, v74, v124, v125
	v_max3_f32 v74, v74, v126, v127
	v_mov_b32_e32 v75, v74
	s_nop 1
	v_permlane32_swap_b32_e32 v74, v75
	v_mfma_f32_32x32x16_bf16 v[48:63], v[240:243], v[248:251], v[48:63]
	v_exp_f32_e32 v240, v136
	v_exp_f32_e32 v242, v137
	v_exp_f32_e32 v241, v139
	v_exp_f32_e32 v243, v135
	v_max_f32_e32 v75, v75, v75
	v_max_f32_e32 v74, v74, v74
	v_max_f32_e32 v74, v74, v75
	v_cmp_ge_f32_e32 vcc, s5, v74
	s_cmp_eq_u64 vcc, exec
	s_cbranch_scc0 .LBB0_109
	v_mov_b32_e32 v232, 1.0

; __device__ __forceinline__ void finishSM(f32x16& p0, f32x16& p1, float alpha, float& l_reg, bf16x8& pa0, bf16x8& pa1, bf16x8& pa2, bf16x8& pa3) {
;   for (int r = 0; r < 16; ++r) p1[r] = __builtin_amdgcn_exp2f(p1[r]);
;   float ps = 0; for (int r = 0; r < 16; ++r) ps += p0[r]; for (int r = 0; r < 16; ++r) ps += p1[r];
;   { auto rr = __builtin_amdgcn_permlane32_swap(__float_as_uint(ps), __float_as_uint(ps), false, false);
;     ps = __uint_as_float(rr[0]) + __uint_as_float(rr[1]); }
;   l_reg = l_reg * alpha + ps;
;     ...
;   PK4(p0, 0, pa0); PK4(p0, 8, pa1); PK4(p1, 0, pa2); PK4(p1, 8, pa3);
;     ...
; }
; __device__ __forceinline__ void qkt(f32x16& p0, f32x16& p1, const bf16* Ks, const bf16x8* qr, const f32x16& negm, int r32, int hi) {
; #pragma unroll
;   for (int d0 = 0; d0 < 8; ++d0) { int cb = (d0 * 16 + hi * 8) * 2;
;     bf16x8 b0 = *reinterpret_cast<const bf16x8*>((const char*)Ks + KSWZ(r32, cb));
;     bf16x8 b1 = *reinterpret_cast<const bf16x8*>((const char*)Ks + KSWZ(32 + r32, cb));
;     if (d0 == 0) { p0 = __builtin_amdgcn_mfma_f32_32x32x16_bf16(b0, qr[0], negm, 0, 0, 0); p1 = __builtin_amdgcn_mfma_f32_32x32x16_bf16(b1, qr[0], negm, 0, 0, 0); }
;     else { p0 = __builtin_amdgcn_mfma_f32_32x32x16_bf16(b0, qr[d0], p0, 0, 0, 0); p1 = __builtin_amdgcn_mfma_f32_32x32x16_bf16(b1, qr[d0], p1, 0, 0, 0); } }
; }
.LBB0_102:
	s_waitcnt vmcnt(2)
	s_waitcnt lgkmcnt(0)
	s_barrier
	ds_read_b128 v[186:189], v216 offset:40960
	ds_read_b128 v[96:99], v216 offset:32768
	v_add_f32_e32 v182, 0, v178
	v_add_f32_e32 v182, v246, v182
	v_add_f32_e32 v182, v179, v182
	v_add_f32_e32 v182, v245, v182
	s_waitcnt lgkmcnt(0)
	v_mfma_f32_32x32x16_bf16 v[128:143], v[96:99], v[146:149], v[80:95]
	v_add_f32_e32 v182, v180, v182
	v_add_f32_e32 v182, v244, v182
	v_add_f32_e32 v182, v181, v182
	v_add_f32_e32 v182, v243, v182
	v_add_f32_e32 v182, v240, v182
	v_add_f32_e32 v182, v242, v182
	v_add_f32_e32 v182, v239, v182
	v_mfma_f32_32x32x16_bf16 v[96:111], v[186:189], v[146:149], v[80:95]
	ds_read_b128 v[186:189], v224 offset:40960
	ds_read_b128 v[204:207], v224 offset:32768
	v_add_f32_e32 v182, v241, v182
	v_exp_f32_e32 v112, v112
	v_add_f32_e32 v182, v236, v182
	v_exp_f32_e32 v113, v113
	v_add_f32_e32 v182, v238, v182
	v_exp_f32_e32 v114, v114
	s_waitcnt lgkmcnt(0)
	v_mfma_f32_32x32x16_bf16 v[128:143], v[204:207], v[150:153], v[128:143]
	v_add_f32_e32 v182, v235, v182
	v_exp_f32_e32 v115, v115
	v_add_f32_e32 v182, v237, v182
	v_exp_f32_e32 v116, v116
	v_add_f32_e32 v182, v112, v182
	v_exp_f32_e32 v117, v117
	v_add_f32_e32 v182, v113, v182
	v_mfma_f32_32x32x16_bf16 v[96:111], v[186:189], v[150:153], v[96:111]
	ds_read_b128 v[186:189], v223 offset:40960
	ds_read_b128 v[204:207], v223 offset:32768
	v_exp_f32_e32 v118, v118
	v_add_f32_e32 v182, v114, v182
	v_exp_f32_e32 v119, v119
	v_add_f32_e32 v182, v115, v182
	v_exp_f32_e32 v120, v120
	v_add_f32_e32 v182, v116, v182
	s_waitcnt lgkmcnt(0)
	v_mfma_f32_32x32x16_bf16 v[128:143], v[204:207], v[154:157], v[128:143]
	v_exp_f32_e32 v121, v121
	v_add_f32_e32 v182, v117, v182
	v_exp_f32_e32 v122, v122
	v_add_f32_e32 v182, v118, v182
	v_exp_f32_e32 v123, v123
	v_add_f32_e32 v182, v119, v182
	v_exp_f32_e32 v124, v124
	v_mfma_f32_32x32x16_bf16 v[96:111], v[186:189], v[154:157], v[96:111]
	ds_read_b128 v[186:189], v221 offset:40960
	ds_read_b128 v[204:207], v221 offset:32768
	v_add_f32_e32 v182, v120, v182
	v_exp_f32_e32 v125, v125
	v_add_f32_e32 v182, v121, v182
	v_exp_f32_e32 v126, v126
	v_add_f32_e32 v182, v122, v182
	v_exp_f32_e32 v127, v127
	s_waitcnt lgkmcnt(0)
	v_mfma_f32_32x32x16_bf16 v[128:143], v[204:207], v[158:161], v[128:143]
	v_add_f32_e32 v182, v123, v182
	v_add_f32_e32 v182, v124, v182
	v_add_f32_e32 v182, v125, v182
	v_add_f32_e32 v182, v126, v182
	v_add_f32_e32 v233, v127, v182
	v_mov_b32_e32 v234, v233
	s_nop 1
	v_permlane32_swap_b32_e32 v233, v234
	v_mfma_f32_32x32x16_bf16 v[96:111], v[186:189], v[158:161], v[96:111]
	ds_read_b128 v[186:189], v222 offset:40960
	ds_read_b128 v[204:207], v222 offset:32768
	s_waitcnt lgkmcnt(0)
	v_mfma_f32_32x32x16_bf16 v[128:143], v[204:207], v[162:165], v[128:143]
	v_mfma_f32_32x32x16_bf16 v[96:111], v[186:189], v[162:165], v[96:111]
	ds_read_b128 v[186:189], v225 offset:40960
	ds_read_b128 v[204:207], v225 offset:32768
	s_waitcnt lgkmcnt(0)
	v_mfma_f32_32x32x16_bf16 v[128:143], v[204:207], v[166:169], v[128:143]
	v_mfma_f32_32x32x16_bf16 v[96:111], v[186:189], v[166:169], v[96:111]
	ds_read_b128 v[186:189], v226 offset:40960
	ds_read_b128 v[204:207], v226 offset:32768
	s_waitcnt lgkmcnt(0)
	v_mfma_f32_32x32x16_bf16 v[128:143], v[204:207], v[170:173], v[128:143]
	v_mfma_f32_32x32x16_bf16 v[96:111], v[186:189], v[170:173], v[96:111]
	ds_read_b128 v[186:189], v227 offset:40960
	ds_read_b128 v[204:207], v227 offset:32768
	v_cvt_pk_bf16_f32 v178, v178, v246
	v_cvt_pk_bf16_f32 v179, v179, v245
	v_cvt_pk_bf16_f32 v180, v180, v244
	v_cvt_pk_bf16_f32 v181, v181, v243
	s_nop 0
	v_permlane32_swap_b32_e32 v178, v180
	s_waitcnt lgkmcnt(0)
	v_mfma_f32_32x32x16_bf16 v[128:143], v[204:207], v[174:177], v[128:143]
	v_permlane32_swap_b32_e32 v179, v181
	v_mfma_f32_32x32x16_bf16 v[96:111], v[186:189], v[174:177], v[96:111]
	v_cvt_pk_bf16_f32 v186, v240, v242
	v_cvt_pk_bf16_f32 v187, v239, v241
	v_cvt_pk_bf16_f32 v188, v236, v238
	v_cvt_pk_bf16_f32 v189, v235, v237
	v_cvt_pk_bf16_f32 v204, v112, v113
	v_cvt_pk_bf16_f32 v205, v114, v115
	v_cvt_pk_bf16_f32 v206, v116, v117
	v_cvt_pk_bf16_f32 v207, v118, v119
	v_cvt_pk_bf16_f32 v236, v120, v121
	v_cvt_pk_bf16_f32 v237, v122, v123
	v_cvt_pk_bf16_f32 v238, v124, v125
	v_cvt_pk_bf16_f32 v239, v126, v127
	s_nop 0
	v_permlane32_swap_b32_e32 v186, v188
	v_permlane32_swap_b32_e32 v187, v189
	v_permlane32_swap_b32_e32 v204, v206
	v_permlane32_swap_b32_e32 v205, v207
	v_permlane32_swap_b32_e32 v236, v238
	v_permlane32_swap_b32_e32 v237, v239
	s_mov_b32 s58, s90
	s_mov_b32 s59, s91
	ds_read_b64_tr_b16 v[240:241], v212 offset:0
	ds_read_b64_tr_b16 v[242:243], v212 offset:0x800
	ds_read_b64_tr_b16 v[244:245], v212 offset:0x1000
	ds_read_b64_tr_b16 v[246:247], v212 offset:0x1800
	ds_read_b64_tr_b16 v[248:249], v212 offset:0x2000
	ds_read_b64_tr_b16 v[250:251], v212 offset:0x2800
	ds_read_b64_tr_b16 v[182:183], v212 offset:0x3000
	ds_read_b64_tr_b16 v[184:185], v212 offset:0x3800
	s_waitcnt lgkmcnt(0)
; template <bool FIRST>
; __device__ __forceinline__ void partialSM(f32x16& p0, f32x16& p1, float& m_reg, f32x16& negm, float& alpha) {
;   float pmax = p0[0]; for (int r = 1; r < 16; ++r) pmax = fmaxf(pmax, p0[r]); for (int r = 0; r < 16; ++r) pmax = fmaxf(pmax, p1[r]);
;   { auto rr = __builtin_amdgcn_permlane32_swap(__float_as_uint(pmax), __float_as_uint(pmax), false, false);
;     pmax = fmaxf(__uint_as_float(rr[0]), __uint_as_float(rr[1])); }
;   if (!FIRST && __builtin_expect(__all(pmax <= THRL), 1)) { alpha = 1.f; }
;   else {
;     const float d = FIRST ? pmax : fmaxf(pmax, 0.f);
;     alpha = FIRST ? 1.f : __builtin_amdgcn_exp2f(-d);
;     m_reg += d;
;     for (int r = 0; r < 16; ++r) p0[r] -= d; for (int r = 0; r < 16; ++r) p1[r] -= d;
;     const float nm = -m_reg; for (int r = 0; r < 16; ++r) negm[r] = nm;
;   }
;   for (int r = 0; r < 16; ++r) p0[r] = __builtin_amdgcn_exp2f(p0[r]);
	s_nop 0
	v_mfma_f32_32x32x16_bf16 v[0:15], v[178:181], v[240:243], v[0:15]
	v_mfma_f32_32x32x16_bf16 v[0:15], v[186:189], v[244:247], v[0:15]
	v_mfma_f32_32x32x16_bf16 v[0:15], v[204:207], v[248:251], v[0:15]
	v_mfma_f32_32x32x16_bf16 v[0:15], v[236:239], v[182:185], v[0:15]
	ds_read_b64_tr_b16 v[182:183], v212 offset:0x200
	ds_read_b64_tr_b16 v[184:185], v212 offset:0xa00
	ds_read_b64_tr_b16 v[240:241], v212 offset:0x1200
	ds_read_b64_tr_b16 v[242:243], v212 offset:0x1a00
	ds_read_b64_tr_b16 v[244:245], v212 offset:0x2200
	ds_read_b64_tr_b16 v[246:247], v212 offset:0x2a00
	ds_read_b64_tr_b16 v[248:249], v212 offset:0x3200
	ds_read_b64_tr_b16 v[250:251], v212 offset:0x3a00
	s_add_i32 m0, s98, 0xc000
	s_nop 0
	buffer_load_dwordx4 v64, s[56:59], s1 offen lds
	s_add_i32 m0, s98, 0xc400
	s_nop 0
	buffer_load_dwordx4 v65, s[56:59], s1 offen lds
	s_waitcnt lgkmcnt(0)
	s_nop 0
	v_mfma_f32_32x32x16_bf16 v[32:47], v[178:181], v[182:185], v[32:47]
	ds_read_b64_tr_b16 v[182:183], v212 offset:0x400
	ds_read_b64_tr_b16 v[184:185], v212 offset:0xc00
	v_mfma_f32_32x32x16_bf16 v[32:47], v[186:189], v[240:243], v[32:47]
	ds_read_b64_tr_b16 v[240:241], v212 offset:0x1400
	ds_read_b64_tr_b16 v[242:243], v212 offset:0x1c00
	v_mfma_f32_32x32x16_bf16 v[32:47], v[204:207], v[244:247], v[32:47]
	ds_read_b64_tr_b16 v[244:245], v212 offset:0x2400
	ds_read_b64_tr_b16 v[246:247], v212 offset:0x2c00
	v_mfma_f32_32x32x16_bf16 v[32:47], v[236:239], v[248:251], v[32:47]
	ds_read_b64_tr_b16 v[248:249], v212 offset:0x3400
	ds_read_b64_tr_b16 v[250:251], v212 offset:0x3c00
	s_waitcnt lgkmcnt(0)
	v_mfma_f32_32x32x16_bf16 v[16:31], v[178:181], v[182:185], v[16:31]
	ds_read_b64_tr_b16 v[182:183], v212 offset:0x600
	ds_read_b64_tr_b16 v[184:185], v212 offset:0xe00
	v_mfma_f32_32x32x16_bf16 v[16:31], v[186:189], v[240:243], v[16:31]
	ds_read_b64_tr_b16 v[240:241], v212 offset:0x1600
	ds_read_b64_tr_b16 v[242:243], v212 offset:0x1e00
	v_mfma_f32_32x32x16_bf16 v[16:31], v[204:207], v[244:247], v[16:31]
	ds_read_b64_tr_b16 v[244:245], v212 offset:0x2600
	ds_read_b64_tr_b16 v[246:247], v212 offset:0x2e00
	v_mfma_f32_32x32x16_bf16 v[16:31], v[236:239], v[248:251], v[16:31]
	ds_read_b64_tr_b16 v[248:249], v212 offset:0x3600
	ds_read_b64_tr_b16 v[250:251], v212 offset:0x3e00
	s_waitcnt lgkmcnt(0)
	s_barrier
	v_mfma_f32_32x32x16_bf16 v[48:63], v[178:181], v[182:185], v[48:63]
	s_add_i32 m0, s98, 0x4000
	s_nop 0
	buffer_load_dwordx4 v66, s[88:91], s1 offen lds
	v_max_f32_e32 v74, v129, v129
	v_max_f32_e32 v75, v128, v128
	v_max_f32_e32 v74, v75, v74
	v_exp_f32_e32 v179, v130
	v_exp_f32_e32 v180, v132
	v_max3_f32 v74, v74, v130, v131
	v_max3_f32 v74, v74, v132, v133
	v_exp_f32_e32 v181, v134
	v_max3_f32 v74, v74, v134, v135
	v_max3_f32 v74, v74, v136, v137
	v_mfma_f32_32x32x16_bf16 v[48:63], v[186:189], v[240:243], v[48:63]
	s_add_i32 m0, s98, 0x4400
	s_nop 0
	buffer_load_dwordx4 v67, s[88:91], s1 offen lds
	v_exp_f32_e32 v240, v136
	v_exp_f32_e32 v242, v137
	v_max3_f32 v74, v74, v138, v139
	v_max3_f32 v74, v74, v140, v141
	v_exp_f32_e32 v241, v139
	v_exp_f32_e32 v243, v135
	v_max3_f32 v74, v74, v142, v143
	v_max3_f32 v74, v74, v96, v97
	v_max3_f32 v74, v74, v98, v99
	v_max3_f32 v74, v74, v100, v101
	v_max3_f32 v74, v74, v102, v103
	v_mfma_f32_32x32x16_bf16 v[48:63], v[204:207], v[244:247], v[48:63]
	v_exp_f32_e32 v244, v133
	v_exp_f32_e32 v245, v128
	v_max3_f32 v74, v74, v104, v105
	v_max3_f32 v74, v74, v106, v107
	v_exp_f32_e32 v246, v131
	v_exp_f32_e32 v247, v129
	v_max3_f32 v74, v74, v108, v109
	v_max3_f32 v74, v74, v110, v111
	v_mov_b32_e32 v75, v74
	s_nop 1
	v_permlane32_swap_b32_e32 v74, v75
	v_mfma_f32_32x32x16_bf16 v[48:63], v[236:239], v[248:251], v[48:63]
	v_exp_f32_e32 v236, v140
	v_exp_f32_e32 v238, v141
	v_exp_f32_e32 v239, v138
	v_exp_f32_e32 v237, v143
	v_exp_f32_e32 v235, v142
	v_max_f32_e32 v75, v75, v75
	v_max_f32_e32 v74, v74, v74
	v_max_f32_e32 v75, v74, v75
	v_cmp_ge_f32_e32 vcc, s5, v75
	s_cmp_eq_u64 vcc, exec
	v_mov_b32_e32 v178, 1.0
	s_cbranch_scc0 .LBB0_110

; template <bool FIRST>
; __device__ __forceinline__ void partialSM(f32x16& p0, f32x16& p1, float& m_reg, f32x16& negm, float& alpha) {
;     ...
;   if (!FIRST && __builtin_expect(__all(pmax <= THRL), 1)) { alpha = 1.f; }
;   else {
;     const float d = FIRST ? pmax : fmaxf(pmax, 0.f);
;     alpha = FIRST ? 1.f : __builtin_amdgcn_exp2f(-d);
;     m_reg += d;
;     for (int r = 0; r < 16; ++r) p0[r] -= d; for (int r = 0; r < 16; ++r) p1[r] -= d;
;     const float nm = -m_reg; for (int r = 0; r < 16; ++r) negm[r] = nm;
;   }
;   for (int r = 0; r < 16; ++r) p0[r] = __builtin_amdgcn_exp2f(p0[r]);
.LBB0_107:
	v_add_f32_e32 v112, v230, v231
	v_fmac_f32_e32 v112, v228, v193
	v_add_f32_e32 v193, v233, v234
	s_add_i32 s0, s0, 2
	s_add_i32 s1, s1, 0x10000
	v_fmac_f32_e32 v193, v112, v232
	s_cmp_gt_u32 s0, 60
	s_waitcnt vmcnt(2)
	s_waitcnt lgkmcnt(0)
	s_barrier
	s_cbranch_scc1 .LBB0_111
	v_mov_b32_e32 v228, v178
	s_branch .LBB0_96
.LBB0_109:
	v_max_f32_e32 v68, v74, v74
	v_max_f32_e32 v68, 0, v68
	v_exp_f32_e64 v232, -v68
	v_add_f32_e32 v229, v229, v68
	v_pk_add_f32 v[128:129], v[128:129], v[68:69] op_sel_hi:[1,0] neg_lo:[0,1] neg_hi:[0,1]
	v_pk_add_f32 v[130:131], v[130:131], v[68:69] op_sel_hi:[1,0] neg_lo:[0,1] neg_hi:[0,1]
	v_pk_add_f32 v[132:133], v[132:133], v[68:69] op_sel_hi:[1,0] neg_lo:[0,1] neg_hi:[0,1]
	v_pk_add_f32 v[134:135], v[134:135], v[68:69] op_sel_hi:[1,0] neg_lo:[0,1] neg_hi:[0,1]
	v_pk_add_f32 v[136:137], v[136:137], v[68:69] op_sel_hi:[1,0] neg_lo:[0,1] neg_hi:[0,1]
	v_pk_add_f32 v[138:139], v[138:139], v[68:69] op_sel_hi:[1,0] neg_lo:[0,1] neg_hi:[0,1]
	v_pk_add_f32 v[140:141], v[140:141], v[68:69] op_sel_hi:[1,0] neg_lo:[0,1] neg_hi:[0,1]
	v_pk_add_f32 v[142:143], v[142:143], v[68:69] op_sel_hi:[1,0] neg_lo:[0,1] neg_hi:[0,1]
	v_sub_f32_e32 v127, v127, v68
	v_sub_f32_e32 v126, v126, v68
	v_sub_f32_e32 v125, v125, v68
	v_sub_f32_e32 v124, v124, v68
	v_sub_f32_e32 v123, v123, v68
	v_sub_f32_e32 v122, v122, v68
	v_sub_f32_e32 v121, v121, v68
	v_sub_f32_e32 v120, v120, v68
	v_sub_f32_e32 v119, v119, v68
	v_sub_f32_e32 v118, v118, v68
	v_sub_f32_e32 v117, v117, v68
	v_sub_f32_e32 v116, v116, v68
	v_sub_f32_e32 v115, v115, v68
	v_sub_f32_e32 v114, v114, v68
	v_sub_f32_e32 v113, v113, v68
	v_sub_f32_e32 v112, v112, v68
	v_xor_b32_e32 v68, 0x80000000, v229
	v_mov_b32_e32 v80, v68
	v_mov_b32_e32 v81, v68
	v_mov_b32_e32 v82, v68
	v_mov_b32_e32 v83, v68
	v_mov_b32_e32 v84, v68
	v_mov_b32_e32 v85, v68
	v_mov_b32_e32 v86, v68
	v_mov_b32_e32 v87, v68
	v_mov_b32_e32 v88, v68
	v_mov_b32_e32 v89, v68
	v_mov_b32_e32 v90, v68
	v_mov_b32_e32 v91, v68
	v_mov_b32_e32 v92, v68
	v_mov_b32_e32 v93, v68
	v_mov_b32_e32 v94, v68
	v_mov_b32_e32 v95, v68
	v_exp_f32_e32 v178, v128
	v_exp_f32_e32 v179, v130
	v_exp_f32_e32 v246, v129
	v_exp_f32_e32 v245, v131
	v_exp_f32_e32 v180, v132
	v_exp_f32_e32 v244, v133
	v_exp_f32_e32 v181, v134
	v_exp_f32_e32 v243, v135
	v_exp_f32_e32 v240, v136
	v_exp_f32_e32 v242, v137
	v_exp_f32_e32 v239, v138
	v_exp_f32_e32 v241, v139
	v_exp_f32_e32 v236, v140
	v_exp_f32_e32 v238, v141
	v_exp_f32_e32 v235, v142
	v_exp_f32_e32 v237, v143
	s_branch .LBB0_98
.LBB0_110:
	v_max_f32_e32 v68, v75, v75
	v_max_f32_e32 v68, 0, v68
	v_exp_f32_e64 v178, -v68
	v_add_f32_e32 v229, v229, v68
	v_pk_add_f32 v[128:129], v[128:129], v[68:69] op_sel_hi:[1,0] neg_lo:[0,1] neg_hi:[0,1]
	v_pk_add_f32 v[130:131], v[130:131], v[68:69] op_sel_hi:[1,0] neg_lo:[0,1] neg_hi:[0,1]
	v_pk_add_f32 v[132:133], v[132:133], v[68:69] op_sel_hi:[1,0] neg_lo:[0,1] neg_hi:[0,1]
	v_pk_add_f32 v[134:135], v[134:135], v[68:69] op_sel_hi:[1,0] neg_lo:[0,1] neg_hi:[0,1]
	v_pk_add_f32 v[136:137], v[136:137], v[68:69] op_sel_hi:[1,0] neg_lo:[0,1] neg_hi:[0,1]
	v_pk_add_f32 v[138:139], v[138:139], v[68:69] op_sel_hi:[1,0] neg_lo:[0,1] neg_hi:[0,1]
	v_pk_add_f32 v[140:141], v[140:141], v[68:69] op_sel_hi:[1,0] neg_lo:[0,1] neg_hi:[0,1]
	v_pk_add_f32 v[142:143], v[142:143], v[68:69] op_sel_hi:[1,0] neg_lo:[0,1] neg_hi:[0,1]
	v_sub_f32_e32 v111, v111, v68
	v_sub_f32_e32 v110, v110, v68
	v_sub_f32_e32 v109, v109, v68
	v_sub_f32_e32 v108, v108, v68
	v_sub_f32_e32 v107, v107, v68
	v_sub_f32_e32 v106, v106, v68
	v_sub_f32_e32 v105, v105, v68
	v_sub_f32_e32 v104, v104, v68
	v_sub_f32_e32 v103, v103, v68
	v_sub_f32_e32 v102, v102, v68
	v_sub_f32_e32 v101, v101, v68
	v_sub_f32_e32 v100, v100, v68
	v_sub_f32_e32 v99, v99, v68
	v_sub_f32_e32 v98, v98, v68
	v_sub_f32_e32 v97, v97, v68
	v_sub_f32_e32 v96, v96, v68
	v_xor_b32_e32 v68, 0x80000000, v229
	v_mov_b32_e32 v80, v68
	v_mov_b32_e32 v81, v68
	v_mov_b32_e32 v82, v68
	v_mov_b32_e32 v83, v68
	v_mov_b32_e32 v84, v68
	v_mov_b32_e32 v85, v68
	v_mov_b32_e32 v86, v68
	v_mov_b32_e32 v87, v68
	v_mov_b32_e32 v88, v68
	v_mov_b32_e32 v89, v68
	v_mov_b32_e32 v90, v68
	v_mov_b32_e32 v91, v68
	v_mov_b32_e32 v92, v68
	v_mov_b32_e32 v93, v68
	v_mov_b32_e32 v94, v68
	v_mov_b32_e32 v95, v68
	v_exp_f32_e32 v245, v128
	v_exp_f32_e32 v247, v129
	v_exp_f32_e32 v179, v130
	v_exp_f32_e32 v246, v131
	v_exp_f32_e32 v180, v132
	v_exp_f32_e32 v244, v133
	v_exp_f32_e32 v181, v134
	v_exp_f32_e32 v243, v135
	v_exp_f32_e32 v240, v136
	v_exp_f32_e32 v242, v137
	v_exp_f32_e32 v239, v138
	v_exp_f32_e32 v241, v139
	v_exp_f32_e32 v236, v140
	v_exp_f32_e32 v238, v141
	v_exp_f32_e32 v235, v142
	v_exp_f32_e32 v237, v143
	s_branch .LBB0_103
